# v61 + attention prologue: V0/K1/K2 DMAs issued after the CL loop so step 0 waits only for K0+Q+CL
# speedup vs baseline: 1.0117x; 1.0081x over previous
.LBB0_546:
	s_and_b32 s77, s76, 1
	s_lshl_b32 s0, s77, 2
	s_add_i32 s8, s0, 0
	s_add_i32 s0, s8, 0x26820
	v_mov_b32_e32 v0, s0
	ds_read_b32 v0, v0
	s_mov_b64 s[0:1], -1
	s_waitcnt lgkmcnt(0)
	v_readfirstlane_b32 s9, v0
	s_cmpk_gt_i32 s9, 0x3ff
	s_cbranch_scc1 .LBB0_545
	s_ashr_i32 s0, s9, 6
	s_lshl_b32 s0, s0, 2
	s_add_i32 s0, s0, 0
	s_add_i32 s0, s0, 0x26840
	v_mov_b32_e32 v0, s0
	ds_read_b32 v0, v0
	v_mov_b32_e32 v48, v196
	s_add_i32 s1, s8, 0x26800
	s_waitcnt lgkmcnt(0)
	v_readfirstlane_b32 s0, v0
	v_readfirstlane_b32 s15, v48
	v_mov_b32_e32 v0, s1
	s_not_b32 s1, s9
	s_ashr_i32 s78, s15, 6
	s_lshl_b32 s1, s1, 8
	s_and_b32 s79, s1, 0x3f00
	s_lshl_b32 s82, s78, 5
	s_add_i32 s8, s82, s79
	s_ashr_i32 s9, s8, 31
	ds_read_b32 v0, v0
	s_lshl_b64 s[8:9], s[8:9], 11
	s_add_u32 s1, s42, s8
	s_addc_u32 s11, s43, s9
	s_lshl_b32 s8, s0, 6
	s_ashr_i32 s9, s8, 31
	s_lshl_b64 s[12:13], s[8:9], 1
	s_waitcnt lgkmcnt(0)
	v_readfirstlane_b32 s10, v0
	s_add_u32 s8, s1, s12
	s_addc_u32 s9, s11, s13
	s_ashr_i32 s11, s10, 31
	s_lshl_b64 s[16:17], s[10:11], 17
	s_add_u32 s1, s44, s16
	s_addc_u32 s11, s45, s17
	s_add_u32 s56, s1, s12
	s_addc_u32 s57, s11, s13
	s_add_u32 s1, s46, s16
	v_and_b32_e32 v206, 63, v48
	s_addc_u32 s11, s47, s17
	s_add_u32 s16, s1, s12
	v_lshlrev_b32_e32 v0, 11, v206
	s_addc_u32 s17, s11, s13
	v_lshl_add_u64 v[2:3], s[56:57], 0, v[0:1]
	s_lshl_b32 s1, s78, 4
	v_bfe_u32 v0, v48, 2, 4
	s_lshl_b32 s56, s78, 3
	v_and_or_b32 v0, s1, 48, v0
	s_ashr_i32 s57, s56, 31
	v_lshlrev_b32_e32 v0, 11, v0
	s_ashr_i32 s1, s15, 3
	v_lshl_add_u64 v[198:199], s[56:57], 1, v[2:3]
	v_lshl_add_u64 v[2:3], s[16:17], 0, v[0:1]
	s_and_b32 s16, s1, 0xffffffe0
	s_ashr_i32 s17, s16, 31
	s_lshl_b32 s14, s78, 10
	v_lshlrev_b32_e32 v0, 3, v48
	s_cmp_lg_u32 0, -1
	v_and_b32_e32 v209, 24, v0
	s_cselect_b32 s1, 0, 0
	v_and_b32_e32 v207, 31, v48
	v_lshl_add_u64 v[2:3], s[16:17], 1, v[2:3]
	v_lshlrev_b32_e32 v0, 1, v209
	s_add_i32 s83, s14, s1
	s_mov_b32 s1, m0
	s_mov_b32 m0, s83
	s_nop 0
	global_load_lds_dwordx4 v[198:199], off
	s_mov_b32 m0, s1
	v_bfe_u32 v208, v48, 5, 1
	v_lshl_add_u64 v[200:201], v[2:3], 0, v[0:1]
	s_add_i32 s84, s83, 0x6000
	v_lshlrev_b32_e32 v0, 11, v207
	v_lshl_or_b32 v0, v208, 4, v0
	global_load_dwordx4 v[124:127], v0, s[8:9]
	global_load_dwordx4 v[120:123], v0, s[8:9] offset:32
	global_load_dwordx4 v[116:119], v0, s[8:9] offset:64
	global_load_dwordx4 v[112:115], v0, s[8:9] offset:96
	s_add_i32 s11, s79, 0x100
	s_lshl_b32 s16, s10, 6
	s_sub_i32 s20, s11, s16
	v_cmp_gt_i32_e32 vcc, s20, v48
	s_and_saveexec_b64 s[60:61], vcc
	s_cbranch_execz .LBB0_556
	s_lshl_b32 s1, s77, 10
	s_add_i32 s56, s1, 0
	s_ashr_i32 s1, s0, 31
	s_add_i32 s56, s56, 0x24800
	s_lshl_b64 s[0:1], s[0:1], 16
	s_add_u32 s33, s38, s0
	s_addc_u32 s57, s39, s1
	s_ashr_i32 s17, s16, 31
	s_lshl_b64 s[8:9], s[16:17], 2
	s_add_u32 s62, s33, s8
	s_addc_u32 s63, s57, s9
	s_add_u32 s8, s38, s8
	s_addc_u32 s9, s39, s9
	s_add_u32 s0, s8, s0
	v_ashrrev_i32_e32 v49, 31, v48
	s_addc_u32 s1, s9, s1
	v_lshl_add_u32 v0, v48, 2, s69
	v_lshl_add_u64 v[2:3], v[48:49], 2, s[0:1]
	s_mov_b64 s[64:65], 0
	v_mov_b32_e32 v4, v48
	s_branch .LBB0_550

.LBB0_556:
	s_or_b64 exec, exec, s[60:61]
	s_mov_b32 s1, m0
	s_mov_b32 m0, s84
	s_nop 0
	global_load_lds_dwordx4 v[200:201], off
	v_lshl_add_u64 v[2:3], v[198:199], 0, s[22:23]
	s_add_i32 s0, s83, 0x2000
	s_mov_b32 m0, s0
	s_nop 0
	global_load_lds_dwordx4 v[2:3], off
	v_lshl_add_u64 v[2:3], v[198:199], 0, s[24:25]
	s_add_i32 s0, s83, 0x4000
	s_mov_b32 m0, s0
	s_nop 0
	global_load_lds_dwordx4 v[2:3], off
	s_mov_b32 m0, s1
	s_cmp_lt_u32 s15, 64
	s_cselect_b64 s[16:17], -1, 0
	v_cmp_eq_u32_e64 s[8:9], 0, v206
	v_mov_b32_e32 v210, 0
	s_and_b64 s[56:57], s[16:17], s[8:9]
	s_and_saveexec_b64 s[0:1], s[56:57]
	s_cbranch_execz .LBB0_560
.LBB0_560:
	s_or_b64 exec, exec, s[0:1]
	v_lshlrev_b32_e32 v0, 10, v208
	v_lshlrev_b32_e32 v2, 4, v207
	v_add3_u32 v216, 0, v0, v2
	s_waitcnt vmcnt(3) lgkmcnt(0)
	s_barrier
	s_waitcnt vmcnt(3)
	s_and_saveexec_b64 s[0:1], s[56:57]
	s_cbranch_execz .Lmy_w2_skip
	v_mov_b32_e32 v0, 1
	global_atomic_add v210, v1, v0, s[18:19] sc0
